# setup phase weight transposes: removed the wait ladder that drained the NEXT tile's prefetch before storing the current tile; prefetch now waited only at the register hand-over (vmcnt(4))
# baseline (speedup 1.0000x reference)
; __device__ __forceinline__ void tile_store(const TItem& t, int lane, const f32x4 (&v)[8], const float (&gm)[8], LAS float* scr) {
;     { const int n4 = lane & 7, kr = lane >> 3;
; #pragma unroll
;       for (int i = 0; i < 8; ++i) { LAS float* s = scr + (kr + 8 * i) * 33 + 4 * n4; s[0] = v[i][0] * gm[i]; s[1] = v[i][1] * gm[i]; s[2] = v[i][2] * gm[i]; s[3] = v[i][3] * gm[i]; } }
;     asm volatile("s_waitcnt lgkmcnt(0)" ::: "memory");
;     const int c = lane & 7;
; #pragma unroll
;     for (int j = 0; j < 4; ++j) { const int n = (lane >> 3) + 8 * j; const LAS float* s = scr + (8 * c) * 33 + n; const float scale = t.scale;
; __device__ __forceinline__ void transposes_phase(ArgsP a, LAS float* scr, int gw, int NGW, int lane) {
;     constexpr int N_ALL = 8 * 4224 + 2 * 2944;
;     if (gw >= N_ALL) return;
;     TItem cur = titem_decode(a, gw); f32x4 v[8]; float gm[8]; tile_load(cur, lane, v, gm);
.LBB0_156:
	s_lshl_b32 s4, s23, 6
	s_and_b32 s5, s26, 0x60
	s_and_b32 s4, s4, 0xffffff00
	s_or_b32 s5, s5, s31
	s_or_b32 s7, s5, s4
	s_and_b64 s[4:5], s[24:25], exec
	s_mulk_i32 s30, 0x2100
	s_cselect_b32 s58, s7, s26
	s_add_i32 s4, s30, 0
	v_and_b32_e32 v35, 7, v34
	v_lshl_add_u32 v36, v35, 4, s4
	v_mul_u32_u24_e32 v37, 0x84, v66
	v_lshlrev_b32_e32 v34, 3, v35
	v_mul_u32_u24_e32 v35, 0x420, v35
	v_lshlrev_b32_e32 v38, 2, v66
	v_mov_b32_e32 v69, 0
	v_add3_u32 v88, s4, v35, v38
	s_mov_b32 s59, 0x14000
	s_mov_b32 s60, 0xe000
	v_add_u32_e32 v89, v36, v37
	v_lshlrev_b32_e32 v86, 1, v34
	v_mov_b32_e32 v90, 0x3e38aa3b
	s_mov_b32 s61, s8
	s_waitcnt vmcnt(0)
	s_branch .LBB0_158

; __device__ __forceinline__ unsigned cvt_pk_bf16(float lo, float hi) { unsigned r; asm volatile("v_cvt_pk_bf16_f32 %0, %1, %2" : "=v"(r) : "v"(lo), "v"(hi)); return r; }
; __device__ __forceinline__ void tile_store(const TItem& t, int lane, const f32x4 (&v)[8], const float (&gm)[8], LAS float* scr) {
;     { const int n4 = lane & 7, kr = lane >> 3;
; #pragma unroll
;       for (int i = 0; i < 8; ++i) { LAS float* s = scr + (kr + 8 * i) * 33 + 4 * n4; s[0] = v[i][0] * gm[i]; s[1] = v[i][1] * gm[i]; s[2] = v[i][2] * gm[i]; s[3] = v[i][3] * gm[i]; } }
;     asm volatile("s_waitcnt lgkmcnt(0)" ::: "memory");
;     const int c = lane & 7;
; #pragma unroll
;     for (int j = 0; j < 4; ++j) { const int n = (lane >> 3) + 8 * j; const LAS float* s = scr + (8 * c) * 33 + n; const float scale = t.scale;
;         u32x4 o; o.x = cvt_pk_bf16(s[0 * 33] * scale, s[1 * 33] * scale); o.y = cvt_pk_bf16(s[2 * 33] * scale, s[3 * 33] * scale); o.z = cvt_pk_bf16(s[4 * 33] * scale, s[5 * 33] * scale); o.w = cvt_pk_bf16(s[6 * 33] * scale, s[7 * 33] * scale);
;         *(u32x4*)(t.WT + (size_t)(t.orow0 + n) * t.ldt + t.k0 + 8 * c) = o; }
;     asm volatile("s_waitcnt lgkmcnt(0)" ::: "memory");
; }
.LBB0_201:
	v_pk_mul_f32 v[100:101], v[72:73], v[2:3] op_sel_hi:[0,1]
	ds_write2_b32 v89, v100, v101 offset1:1
	v_pk_mul_f32 v[100:101], v[72:73], v[4:5] op_sel_hi:[0,1]
	ds_write2_b32 v89, v100, v101 offset0:2 offset1:3
	v_pk_mul_f32 v[100:101], v[70:71], v[6:7] op_sel_hi:[0,1]
	v_add_u32_e32 v87, 0x420, v89
	ds_write2_b32 v87, v100, v101 offset1:1
	v_pk_mul_f32 v[100:101], v[70:71], v[8:9] op_sel_hi:[0,1]
	v_add_u32_e32 v87, 0x428, v89
	ds_write2_b32 v87, v100, v101 offset1:1
	v_pk_mul_f32 v[100:101], v[76:77], v[10:11] op_sel_hi:[0,1]
	v_add_u32_e32 v87, 0x840, v89
	ds_write2_b32 v87, v100, v101 offset1:1
	v_pk_mul_f32 v[100:101], v[76:77], v[12:13] op_sel_hi:[0,1]
	v_add_u32_e32 v87, 0x848, v89
	ds_write2_b32 v87, v100, v101 offset1:1
	v_pk_mul_f32 v[100:101], v[74:75], v[14:15] op_sel_hi:[0,1]
	v_add_u32_e32 v87, 0xc60, v89
	ds_write2_b32 v87, v100, v101 offset1:1
	v_pk_mul_f32 v[100:101], v[74:75], v[16:17] op_sel_hi:[0,1]
	v_add_u32_e32 v87, 0xc68, v89
	ds_write2_b32 v87, v100, v101 offset1:1
	v_pk_mul_f32 v[100:101], v[80:81], v[18:19] op_sel_hi:[0,1]
	v_add_u32_e32 v87, 0x1080, v89
	ds_write2_b32 v87, v100, v101 offset1:1
	v_pk_mul_f32 v[100:101], v[80:81], v[20:21] op_sel_hi:[0,1]
	v_add_u32_e32 v87, 0x1088, v89
	ds_write2_b32 v87, v100, v101 offset1:1
	v_pk_mul_f32 v[100:101], v[78:79], v[22:23] op_sel_hi:[0,1]
	v_add_u32_e32 v87, 0x14a0, v89
	ds_write2_b32 v87, v100, v101 offset1:1
	v_pk_mul_f32 v[100:101], v[78:79], v[24:25] op_sel_hi:[0,1]
	v_add_u32_e32 v87, 0x14a8, v89
	ds_write2_b32 v87, v100, v101 offset1:1
	v_pk_mul_f32 v[100:101], v[82:83], v[26:27] op_sel_hi:[0,1]
	v_add_u32_e32 v87, 0x18c0, v89
	ds_write2_b32 v87, v100, v101 offset1:1
	v_pk_mul_f32 v[100:101], v[82:83], v[28:29] op_sel_hi:[0,1]
	v_add_u32_e32 v87, 0x18c8, v89
	ds_write2_b32 v87, v100, v101 offset1:1
	v_pk_mul_f32 v[100:101], v[84:85], v[30:31] op_sel_hi:[0,1]
	v_add_u32_e32 v87, 0x1ce0, v89
	ds_write2_b32 v87, v100, v101 offset1:1
	v_pk_mul_f32 v[100:101], v[84:85], v[32:33] op_sel_hi:[0,1]
	v_add_u32_e32 v87, 0x1ce8, v89
	ds_write2_b32 v87, v100, v101 offset1:1
	s_waitcnt lgkmcnt(0)
	ds_read2_b32 v[100:101], v88 offset1:33
	s_ashr_i32 s7, s6, 31
	s_andn2_b64 vcc, exec, s[18:19]
	s_waitcnt lgkmcnt(0)
	v_mul_f32_e32 v87, v71, v100
	v_mul_f32_e32 v100, v71, v101
	v_cvt_pk_bf16_f32 v100, v87, v100
	ds_read2_b32 v[102:103], v88 offset0:66 offset1:99
	s_waitcnt lgkmcnt(0)
	v_mul_f32_e32 v101, v71, v103
	v_mul_f32_e32 v87, v71, v102
	v_cvt_pk_bf16_f32 v101, v87, v101
	ds_read2_b32 v[102:103], v88 offset0:132 offset1:165
	s_waitcnt lgkmcnt(0)
	v_mul_f32_e32 v87, v71, v102
	v_mul_f32_e32 v102, v71, v103
	v_cvt_pk_bf16_f32 v102, v87, v102
	ds_read2_b32 v[104:105], v88 offset0:198 offset1:231
	s_waitcnt lgkmcnt(0)
	v_mul_f32_e32 v87, v71, v104
	v_mul_f32_e32 v103, v71, v105
	v_cvt_pk_bf16_f32 v103, v87, v103
	v_add_u32_e32 v87, s58, v66
	v_mad_u64_u32 v[104:105], s[4:5], v87, s57, 0
	v_ashrrev_i32_e32 v107, 31, v87
	v_mov_b32_e32 v106, v105
	v_mad_u64_u32 v[106:107], s[4:5], v107, s57, v[106:107]
	v_mov_b32_e32 v105, v106
	ds_read2_b32 v[106:107], v88 offset0:8 offset1:41
	v_lshl_add_u64 v[104:105], v[104:105], 1, s[0:1]
	s_lshl_b64 s[4:5], s[6:7], 1
	v_lshl_add_u64 v[104:105], v[104:105], 0, s[4:5]
	v_mov_b32_e32 v87, v69
	v_lshl_add_u64 v[104:105], v[104:105], 0, v[86:87]
	global_store_dwordx4 v[104:105], v[100:103], off
	s_waitcnt lgkmcnt(0)
	s_nop 0
	v_mul_f32_e32 v100, v71, v106
	v_mul_f32_e32 v101, v71, v107
	v_cvt_pk_bf16_f32 v100, v100, v101
	ds_read2_b32 v[102:103], v88 offset0:74 offset1:107
	s_waitcnt lgkmcnt(0)
	v_mul_f32_e32 v101, v71, v102
	v_mul_f32_e32 v102, v71, v103
	v_cvt_pk_bf16_f32 v101, v101, v102
	ds_read2_b32 v[102:103], v88 offset0:140 offset1:173
	s_waitcnt lgkmcnt(0)
	v_mul_f32_e32 v102, v71, v102
	v_mul_f32_e32 v103, v71, v103
	v_cvt_pk_bf16_f32 v102, v102, v103
	ds_read2_b32 v[104:105], v88 offset0:206 offset1:239
	s_waitcnt lgkmcnt(0)
	v_mul_f32_e32 v103, v71, v104
	v_mul_f32_e32 v104, v71, v105
	v_cvt_pk_bf16_f32 v103, v103, v104
	v_add_u32_e32 v104, s58, v73
	v_ashrrev_i32_e32 v107, 31, v104
	v_mad_u64_u32 v[104:105], s[26:27], v104, s57, 0
	v_mov_b32_e32 v106, v105
	v_mad_u64_u32 v[106:107], s[26:27], v107, s57, v[106:107]
	v_mov_b32_e32 v105, v106
	ds_read2_b32 v[106:107], v88 offset0:16 offset1:49
	v_lshl_add_u64 v[104:105], v[104:105], 1, s[0:1]
	v_lshl_add_u64 v[104:105], v[104:105], 0, s[4:5]
	v_lshl_add_u64 v[104:105], v[104:105], 0, v[86:87]
	global_store_dwordx4 v[104:105], v[100:103], off
	s_waitcnt lgkmcnt(0)
	s_nop 0
	v_mul_f32_e32 v100, v71, v106
	v_mul_f32_e32 v101, v71, v107
	v_cvt_pk_bf16_f32 v100, v100, v101
	ds_read2_b32 v[102:103], v88 offset0:82 offset1:115
	s_waitcnt lgkmcnt(0)
	v_mul_f32_e32 v101, v71, v102
	v_mul_f32_e32 v102, v71, v103
	v_cvt_pk_bf16_f32 v101, v101, v102
	ds_read2_b32 v[102:103], v88 offset0:148 offset1:181
	s_waitcnt lgkmcnt(0)
	v_mul_f32_e32 v102, v71, v102
	v_mul_f32_e32 v103, v71, v103
	v_cvt_pk_bf16_f32 v102, v102, v103
	ds_read2_b32 v[104:105], v88 offset0:214 offset1:247
	s_waitcnt lgkmcnt(0)
	v_mul_f32_e32 v103, v71, v104
	v_mul_f32_e32 v104, v71, v105
	v_cvt_pk_bf16_f32 v103, v103, v104
	v_add_u32_e32 v104, s58, v75
	v_ashrrev_i32_e32 v107, 31, v104
	v_mad_u64_u32 v[104:105], s[26:27], v104, s57, 0
	v_mov_b32_e32 v106, v105
	v_mad_u64_u32 v[106:107], s[26:27], v107, s57, v[106:107]
	v_mov_b32_e32 v105, v106
	ds_read2_b32 v[106:107], v88 offset0:24 offset1:57
	v_lshl_add_u64 v[104:105], v[104:105], 1, s[0:1]
	v_lshl_add_u64 v[104:105], v[104:105], 0, s[4:5]
	v_lshl_add_u64 v[104:105], v[104:105], 0, v[86:87]
	global_store_dwordx4 v[104:105], v[100:103], off
	s_waitcnt lgkmcnt(0)
	s_nop 0
	v_mul_f32_e32 v100, v71, v106
	v_mul_f32_e32 v101, v71, v107
	v_cvt_pk_bf16_f32 v100, v100, v101
	ds_read2_b32 v[102:103], v88 offset0:90 offset1:123
	s_waitcnt lgkmcnt(0)
	v_mul_f32_e32 v101, v71, v102
	v_mul_f32_e32 v102, v71, v103
	v_cvt_pk_bf16_f32 v101, v101, v102
	ds_read2_b32 v[102:103], v88 offset0:156 offset1:189
	s_waitcnt lgkmcnt(0)
	v_mul_f32_e32 v102, v71, v102
	v_mul_f32_e32 v103, v71, v103
	v_cvt_pk_bf16_f32 v102, v102, v103
	ds_read2_b32 v[104:105], v88 offset0:222 offset1:255
	s_waitcnt lgkmcnt(0)
	v_mul_f32_e32 v103, v71, v104
	v_mul_f32_e32 v104, v71, v105
	v_cvt_pk_bf16_f32 v103, v103, v104
	v_add_u32_e32 v104, s58, v77
	v_ashrrev_i32_e32 v107, 31, v104
	v_mad_u64_u32 v[104:105], s[26:27], v104, s57, 0
	v_mov_b32_e32 v106, v105
	v_mad_u64_u32 v[106:107], s[26:27], v107, s57, v[106:107]
	v_mov_b32_e32 v105, v106
	v_lshl_add_u64 v[104:105], v[104:105], 1, s[0:1]
	v_lshl_add_u64 v[104:105], v[104:105], 0, s[4:5]
	v_lshl_add_u64 v[104:105], v[104:105], 0, v[86:87]
	global_store_dwordx4 v[104:105], v[100:103], off
	s_waitcnt lgkmcnt(0)
	s_cbranch_vccnz .LBB0_157
; __device__ __forceinline__ void transposes_phase(ArgsP a, LAS float* scr, int gw, int NGW, int lane) {
;     ...
;         if (has) { cur = nxt;
; #pragma unroll
;             for (int i = 0; i < 8; ++i) { v[i] = vn[i]; gm[i] = gn[i]; } }
	s_waitcnt vmcnt(4)
	v_mov_b32_e32 v84, v99
	v_mov_b32_e32 v82, v98
	v_mov_b32_e32 v78, v97
	v_mov_b32_e32 v80, v96
	v_mov_b32_e32 v74, v95
	v_mov_b32_e32 v76, v94
	v_mov_b32_e32 v70, v93
	v_mov_b32_e32 v72, v92
	v_mov_b32_e32 v71, v91
	s_mov_b32 s58, s24
	s_mov_b32 s57, s62
	s_mov_b32 s6, s28
	s_mov_b64 s[0:1], s[22:23]
	v_mov_b32_e32 v2, v34
	v_mov_b32_e32 v3, v35
	v_mov_b32_e32 v4, v36
	v_mov_b32_e32 v5, v37
	v_mov_b32_e32 v6, v42
	v_mov_b32_e32 v7, v43
	v_mov_b32_e32 v8, v44
	v_mov_b32_e32 v9, v45
	v_mov_b32_e32 v10, v38
	v_mov_b32_e32 v11, v39
	v_mov_b32_e32 v12, v40
	v_mov_b32_e32 v13, v41
	v_mov_b32_e32 v14, v50
	v_mov_b32_e32 v15, v51
	v_mov_b32_e32 v16, v52
	v_mov_b32_e32 v17, v53
	v_mov_b32_e32 v18, v46
	v_mov_b32_e32 v19, v47
	v_mov_b32_e32 v20, v48
	v_mov_b32_e32 v21, v49
	v_mov_b32_e32 v22, v58
	v_mov_b32_e32 v23, v59
	v_mov_b32_e32 v24, v60
	v_mov_b32_e32 v25, v61
	v_mov_b32_e32 v26, v54
	v_mov_b32_e32 v27, v55
	v_mov_b32_e32 v28, v56
	v_mov_b32_e32 v29, v57
	v_mov_b32_e32 v30, v62
	v_mov_b32_e32 v31, v63
	v_mov_b32_e32 v32, v64
	v_mov_b32_e32 v33, v65
	s_branch .LBB0_157
